# hand-written RWKV sample units (8 waves prep+scan, next-unit prefetch, one barrier per unit) on top of prompt scan+prep
# speedup vs baseline: 1.1138x; 1.0123x over previous
.LBB0_1289:
.LBB0_1290:
	s_cmp_lt_i32 s50, 7
	s_cselect_b64 s[0:1], -1, 0
	s_and_b64 s[24:25], s[0:1], s[4:5]
	s_andn2_b64 vcc, exec, s[24:25]
	s_cbranch_vccnz .LBB0_1378
	s_cmpk_gt_i32 s2, 0x7ff
	s_cbranch_scc1 .LBB0_1318
	s_and_b32 s52, s2, 15
	v_readfirstlane_b32 s33, v179
	v_mov_b32_e32 v77, 0
	v_and_b32_e32 v184, 63, v178
	v_lshlrev_b32_e32 v230, 1, v184
	v_lshlrev_b32_e32 v231, 2, v184
	v_and_b32_e32 v210, 15, v178
	v_lshrrev_b32_e32 v185, 3, v178
	v_and_b32_e32 v185, 0x3e, v185
	v_lshlrev_b32_e32 v233, 8, v185
	v_lshl_add_u32 v233, v210, 4, v233
	v_lshlrev_b32_e32 v159, 4, v210
	v_lshlrev_b32_e32 v208, 2, v185
	v_add_u32_e32 v208, 0x500, v208
	v_mov_b32_e32 v209, 0x600
	s_movk_i32 s0, 0x5200
	v_mul_lo_u32 v234, v210, s0
	v_lshl_add_u32 v234, v185, 1, v234
	s_mul_i32 s0, s33, 0x610
	v_add_u32_e32 v235, s0, v231
	s_add_i32 s0, s0, 0x600
	v_mov_b32_e32 v244, s0
	v_mov_b32_e32 v162, 0
	v_mov_b32_e32 v163, 0
	v_mov_b32_e32 v164, 0
	v_mov_b32_e32 v165, 0
	v_mov_b32_e32 v173, 0
	v_mov_b32_e32 v166, 0
	v_mov_b32_e32 v167, 0
	v_mov_b32_e32 v168, 0
	v_mov_b32_e32 v169, 0
	v_mov_b32_e32 v170, 0
	v_mov_b32_e32 v171, 0
	v_mov_b32_e32 v172, 0
	v_mov_b32_e32 v174, 0
	v_mov_b32_e32 v175, 0
	v_mov_b32_e32 v176, 0
	v_mov_b32_e32 v177, 0
	v_mov_b32_e32 v186, 0x20020
	v_mov_b32_e32 v187, 0x20080
	v_mov_b32_e32 v188, 0x200b0
	ds_read_b128 v[216:219], v186
	ds_read_b64 v[220:221], v187
	ds_read_b128 v[236:239], v188
	s_waitcnt lgkmcnt(0)
	v_readfirstlane_b32 s54, v216
	v_readfirstlane_b32 s55, v217
	v_readfirstlane_b32 s56, v218
	v_readfirstlane_b32 s57, v219
	v_readfirstlane_b32 s58, v220
	v_readfirstlane_b32 s59, v221
	v_readfirstlane_b32 s60, v236
	v_readfirstlane_b32 s61, v237
	v_readfirstlane_b32 s66, v238
	v_readfirstlane_b32 s67, v239
	s_lshl_b32 s0, s52, 8
	s_add_u32 s58, s58, s0
	s_addc_u32 s59, s59, 0
	global_load_dword v224, v231, s[58:59]
	s_add_u32 s58, s58, 0x1000
	s_addc_u32 s59, s59, 0
	global_load_dword v225, v231, s[58:59]
	s_add_u32 s58, s58, 0x1000
	s_addc_u32 s59, s59, 0
	global_load_dword v226, v231, s[58:59]
	s_add_u32 s60, s60, s0
	s_addc_u32 s61, s61, 0
	global_load_dword v227, v231, s[60:61]
	s_add_u32 s66, s66, s0
	s_addc_u32 s67, s67, 0
	global_load_dword v228, v231, s[66:67]
	s_mov_b32 s53, s2
	s_mov_b32 s99, 0
	s_lshr_b32 s1, s53, 4
	s_lshl_b32 s0, s1, 3
	s_add_i32 s0, s0, 0x4000
	s_add_i32 s66, s0, s33
	s_lshl_b32 s67, s52, 7
	s_lshl_b32 s60, s53, 14
	s_add_u32 s60, s56, s60
	s_addc_u32 s61, s57, 0
	global_load_dwordx4 v[216:219], v233, s[60:61]
	global_load_dwordx4 v[220:223], v233, s[60:61] offset:256
	s_mul_i32 s58, s66, 0x5200
	s_add_u32 s58, s58, s67
	s_add_u32 s58, s58, 0x5203000
	s_add_u32 s58, s46, s58
	s_addc_u32 s59, s47, 0
	global_load_short_d16_hi v162, v230, s[58:59] offset:-2048
	global_load_short_d16_hi v163, v230, s[58:59]
	global_load_short_d16_hi v164, v230, s[58:59] offset:2048
	s_cmp_eq_u32 s33, 0
	s_cbranch_scc1 .Lrws_shift_a
	s_sub_u32 s60, s58, 0x5200
	s_subb_u32 s61, s59, 0
	global_load_short_d16_hi v175, v230, s[60:61] offset:-2048
	global_load_short_d16_hi v176, v230, s[60:61]
	global_load_short_d16_hi v177, v230, s[60:61] offset:2048
	s_branch .Lrws_shiftdone_a
.Lrws_shift_a:
	s_mul_i32 s60, s1, 0x3400
	s_lshl_b32 s61, s52, 8
	s_add_u32 s60, s60, s61
	s_add_u32 s60, s54, s60
	s_addc_u32 s61, s55, 0
	global_load_dword v175, v231, s[60:61]
	s_add_u32 s60, s60, 0x1000
	s_addc_u32 s61, s61, 0
	global_load_dword v176, v231, s[60:61]
	s_add_u32 s60, s60, 0x1000
	s_addc_u32 s61, s61, 0
	global_load_dword v177, v231, s[60:61]
.Lrws_shiftdone_a:
	s_lshl_b32 s60, s66, 11
	s_add_u32 s60, s60, s67
	s_add_u32 s58, s60, 0x3000000
	s_add_u32 s58, s46, s58
	s_addc_u32 s59, s47, 0
	global_load_short_d16_hi v165, v230, s[58:59]
	s_add_u32 s58, s60, 0x1bb00000
	s_add_u32 s58, s46, s58
	s_addc_u32 s59, s47, 0
	global_load_short_d16_hi v173, v230, s[58:59]
	s_lshl_b32 s60, s0, 11
	s_add_u32 s60, s60, s67
	s_add_u32 s60, s60, 0x3000000
	s_add_u32 s60, s46, s60
	s_addc_u32 s61, s47, 0
	global_load_short_d16_hi v166, v230, s[60:61]
	global_load_short_d16_hi v167, v230, s[60:61] offset:2048
	s_add_u32 s60, s60, 0x1000
	s_addc_u32 s61, s61, 0
	global_load_short_d16_hi v168, v230, s[60:61]
	global_load_short_d16_hi v169, v230, s[60:61] offset:2048
	s_add_u32 s60, s60, 0x1000
	s_addc_u32 s61, s61, 0
	global_load_short_d16_hi v170, v230, s[60:61]
	global_load_short_d16_hi v171, v230, s[60:61] offset:2048
	s_add_u32 s60, s60, 0x1000
	s_addc_u32 s61, s61, 0
	global_load_short_d16_hi v172, v230, s[60:61]
	global_load_short_d16_hi v174, v230, s[60:61] offset:2048
	s_lshl_b32 s60, s66, 8
	s_lshl_b32 s61, s52, 4
	s_add_u32 s60, s60, s61
	s_add_u32 s60, s60, 0x1b200000
	s_add_u32 s60, s46, s60
	s_addc_u32 s61, s47, 0
	global_load_dwordx4 v[180:183], v77, s[60:61] offset:-4
	s_waitcnt vmcnt(0)
	v_sub_f32_e32 v229, 1.0, v228
.Lrws_unit:
	s_waitcnt vmcnt(0)
	v_add_u32_e32 v245, s99, v235
	v_add_u32_e32 v246, s99, v244
	v_add_u32_e32 v156, s99, v159
	v_add_u32_e32 v157, s99, v208
	v_add_u32_e32 v158, s99, v209
	v_mov_b32_e32 v100, v216
	v_mov_b32_e32 v101, v220
	v_mov_b32_e32 v102, v217
	v_mov_b32_e32 v103, v221
	v_mov_b32_e32 v104, v218
	v_mov_b32_e32 v105, v222
	v_mov_b32_e32 v106, v219
	v_mov_b32_e32 v107, v223
	s_cmp_gt_u32 s33, 0
	s_cselect_b32 s0, 1.0, 0
	v_mul_f32_e32 v184, s0, v166
	s_cmp_gt_u32 s33, 1
	s_cselect_b32 s0, 1.0, 0
	v_fmac_f32_e32 v184, s0, v167
	s_cmp_gt_u32 s33, 2
	s_cselect_b32 s0, 1.0, 0
	v_fmac_f32_e32 v184, s0, v168
	s_cmp_gt_u32 s33, 3
	s_cselect_b32 s0, 1.0, 0
	v_fmac_f32_e32 v184, s0, v169
	s_cmp_gt_u32 s33, 4
	s_cselect_b32 s0, 1.0, 0
	v_fmac_f32_e32 v184, s0, v170
	s_cmp_gt_u32 s33, 5
	s_cselect_b32 s0, 1.0, 0
	v_fmac_f32_e32 v184, s0, v171
	s_cmp_gt_u32 s33, 6
	s_cselect_b32 s0, 1.0, 0
	v_fmac_f32_e32 v184, s0, v172
	v_mul_f32_e32 v187, 0xbfb8aa3b, v184
	v_mul_f32_e32 v188, 0x3fb8aa3b, v184
	v_mul_f32_e32 v189, 0xbfb8aa3b, v165
	v_mul_f32_e32 v190, 0x3fb8aa3b, v165
	v_exp_f32_e32 v185, v187
	v_exp_f32_e32 v186, v188
	v_exp_f32_e32 v189, v189
	v_exp_f32_e32 v190, v190
	v_sub_f32_e32 v191, v175, v162
	v_sub_f32_e32 v192, v176, v163
	v_sub_f32_e32 v193, v177, v164
	v_fma_f32 v191, v224, v191, v162
	v_fma_f32 v192, v225, v192, v163
	v_fma_f32 v193, v226, v193, v164
	v_mul_f32_e32 v202, v185, v189
	v_mul_f32_e32 v203, v186, v190
	v_mul_f32_e32 v194, v192, v227
	v_fma_f32 v195, v173, v228, v229
	v_mul_f32_e32 v194, v194, v181
	v_mul_f32_e32 v196, v192, v195
	v_mul_f32_e64 v198, -v194, v185
	v_mul_f32_e32 v197, v194, v173
	v_mul_f32_e32 v199, v202, v191
	ds_write2st64_b32 v245, v198, v199 offset0:0 offset1:1
	v_mul_f32_e32 v200, v197, v203
	v_mul_f32_e32 v201, v196, v203
	ds_write2st64_b32 v245, v202, v200 offset0:2 offset1:3
	ds_write2st64_b32 v245, v201, v193 offset0:4 offset1:5
	s_mov_b64 exec, 1
	ds_write_b64 v246, v[182:183]
	s_mov_b64 exec, -1
	s_lshr_b32 s1, s53, 4
	s_lshl_b32 s0, s1, 3
	s_add_i32 s0, s0, 0x4000
	s_mul_i32 s0, s0, 0x5200
	s_lshl_b32 s1, s52, 7
	s_add_u32 s0, s0, s1
	s_add_u32 s0, s0, 0x5201000
	s_add_u32 s100, s46, s0
	s_addc_u32 s101, s47, 0
	s_lshl_b32 s0, s53, 14
	s_add_u32 s0, s0, 0xd4ae000
	s_add_u32 s96, s44, s0
	s_addc_u32 s97, s45, 0
	s_add_i32 s53, s53, s48
	s_cmpk_lt_i32 s53, 0x800
	s_cbranch_scc0 .Lrws_nopf
	s_lshr_b32 s1, s53, 4
	s_lshl_b32 s0, s1, 3
	s_add_i32 s0, s0, 0x4000
	s_add_i32 s66, s0, s33
	s_lshl_b32 s67, s52, 7
	s_lshl_b32 s60, s53, 14
	s_add_u32 s60, s56, s60
	s_addc_u32 s61, s57, 0
	global_load_dwordx4 v[216:219], v233, s[60:61]
	global_load_dwordx4 v[220:223], v233, s[60:61] offset:256
	s_mul_i32 s58, s66, 0x5200
	s_add_u32 s58, s58, s67
	s_add_u32 s58, s58, 0x5203000
	s_add_u32 s58, s46, s58
	s_addc_u32 s59, s47, 0
	global_load_short_d16_hi v162, v230, s[58:59] offset:-2048
	global_load_short_d16_hi v163, v230, s[58:59]
	global_load_short_d16_hi v164, v230, s[58:59] offset:2048
	s_cmp_eq_u32 s33, 0
	s_cbranch_scc1 .Lrws_shift_b
	s_sub_u32 s60, s58, 0x5200
	s_subb_u32 s61, s59, 0
	global_load_short_d16_hi v175, v230, s[60:61] offset:-2048
	global_load_short_d16_hi v176, v230, s[60:61]
	global_load_short_d16_hi v177, v230, s[60:61] offset:2048
	s_branch .Lrws_shiftdone_b

.Lrws_shiftdone_b:
	s_lshl_b32 s60, s66, 11
	s_add_u32 s60, s60, s67
	s_add_u32 s58, s60, 0x3000000
	s_add_u32 s58, s46, s58
	s_addc_u32 s59, s47, 0
	global_load_short_d16_hi v165, v230, s[58:59]
	s_add_u32 s58, s60, 0x1bb00000
	s_add_u32 s58, s46, s58
	s_addc_u32 s59, s47, 0
	global_load_short_d16_hi v173, v230, s[58:59]
	s_lshl_b32 s60, s0, 11
	s_add_u32 s60, s60, s67
	s_add_u32 s60, s60, 0x3000000
	s_add_u32 s60, s46, s60
	s_addc_u32 s61, s47, 0
	global_load_short_d16_hi v166, v230, s[60:61]
	global_load_short_d16_hi v167, v230, s[60:61] offset:2048
	s_add_u32 s60, s60, 0x1000
	s_addc_u32 s61, s61, 0
	global_load_short_d16_hi v168, v230, s[60:61]
	global_load_short_d16_hi v169, v230, s[60:61] offset:2048
	s_add_u32 s60, s60, 0x1000
	s_addc_u32 s61, s61, 0
	global_load_short_d16_hi v170, v230, s[60:61]
	global_load_short_d16_hi v171, v230, s[60:61] offset:2048
	s_add_u32 s60, s60, 0x1000
	s_addc_u32 s61, s61, 0
	global_load_short_d16_hi v172, v230, s[60:61]
	global_load_short_d16_hi v174, v230, s[60:61] offset:2048
	s_lshl_b32 s60, s66, 8
	s_lshl_b32 s61, s52, 4
	s_add_u32 s60, s60, s61
	s_add_u32 s60, s60, 0x1b200000
	s_add_u32 s60, s46, s60
	s_addc_u32 s61, s47, 0
	global_load_dwordx4 v[180:183], v77, s[60:61] offset:-4
.Lrws_nopf:
	s_waitcnt lgkmcnt(0)
	s_barrier
	ds_read_b128 v[108:111], v156 offset:0
	ds_read_b128 v[112:115], v156 offset:256
	ds_read_b128 v[120:123], v156 offset:1024
	ds_read_b64 v[124:125], v157 offset:0
	ds_read_b128 v[116:119], v156 offset:768
	ds_read_b64 v[126:127], v158 offset:0
	s_waitcnt lgkmcnt(0)
	ds_read_b128 v[128:131], v156 offset:1552
	ds_read_b128 v[132:135], v156 offset:1808
	ds_read_b128 v[140:143], v156 offset:2576
	ds_read_b64 v[144:145], v157 offset:1552
	ds_read_b128 v[136:139], v156 offset:2320
	ds_read_b64 v[146:147], v158 offset:1552
	v_pk_mul_f32 v[148:149], v[100:101], v[108:109] op_sel_hi:[1,0]
	v_pk_mul_f32 v[150:151], v[100:101], v[112:113] op_sel_hi:[1,0]
	v_pk_fma_f32 v[148:149], v[102:103], v[108:109], v[148:149] op_sel:[0,1,0]
	v_pk_fma_f32 v[150:151], v[102:103], v[112:113], v[150:151] op_sel:[0,1,0]
	v_pk_fma_f32 v[148:149], v[104:105], v[110:111], v[148:149] op_sel_hi:[1,0,1]
	v_pk_fma_f32 v[150:151], v[104:105], v[114:115], v[150:151] op_sel_hi:[1,0,1]
	v_pk_fma_f32 v[148:149], v[106:107], v[110:111], v[148:149] op_sel:[0,1,0]
	v_pk_fma_f32 v[150:151], v[106:107], v[114:115], v[150:151] op_sel:[0,1,0]
	v_pk_fma_f32 v[100:101], v[124:125], v[120:121], v[100:101] op_sel_hi:[1,0,1]
	v_add_f32_dpp v148, v148, v148 quad_perm:[1,0,3,2] row_mask:0xf bank_mask:0xf bound_ctrl:1
	v_add_f32_dpp v149, v149, v149 quad_perm:[1,0,3,2] row_mask:0xf bank_mask:0xf bound_ctrl:1
	v_add_f32_dpp v150, v150, v150 quad_perm:[1,0,3,2] row_mask:0xf bank_mask:0xf bound_ctrl:1
	v_add_f32_dpp v151, v151, v151 quad_perm:[1,0,3,2] row_mask:0xf bank_mask:0xf bound_ctrl:1
	v_pk_fma_f32 v[102:103], v[124:125], v[120:121], v[102:103] op_sel:[0,1,0]
	v_add_f32_dpp v148, v148, v148 quad_perm:[2,3,0,1] row_mask:0xf bank_mask:0xf bound_ctrl:1
	v_add_f32_dpp v149, v149, v149 quad_perm:[2,3,0,1] row_mask:0xf bank_mask:0xf bound_ctrl:1
	v_add_f32_dpp v150, v150, v150 quad_perm:[2,3,0,1] row_mask:0xf bank_mask:0xf bound_ctrl:1
	v_add_f32_dpp v151, v151, v151 quad_perm:[2,3,0,1] row_mask:0xf bank_mask:0xf bound_ctrl:1
	v_pk_fma_f32 v[104:105], v[124:125], v[122:123], v[104:105] op_sel_hi:[1,0,1]
	v_add_f32_dpp v148, v148, v148 row_half_mirror row_mask:0xf bank_mask:0xf bound_ctrl:1
	v_add_f32_dpp v149, v149, v149 row_half_mirror row_mask:0xf bank_mask:0xf bound_ctrl:1
	v_add_f32_dpp v150, v150, v150 row_half_mirror row_mask:0xf bank_mask:0xf bound_ctrl:1
	v_add_f32_dpp v151, v151, v151 row_half_mirror row_mask:0xf bank_mask:0xf bound_ctrl:1
	v_pk_fma_f32 v[106:107], v[124:125], v[122:123], v[106:107] op_sel:[0,1,0]
	v_add_f32_dpp v148, v148, v148 row_mirror row_mask:0xf bank_mask:0xf bound_ctrl:1
	v_add_f32_dpp v149, v149, v149 row_mirror row_mask:0xf bank_mask:0xf bound_ctrl:1
	v_add_f32_dpp v150, v150, v150 row_mirror row_mask:0xf bank_mask:0xf bound_ctrl:1
	v_pk_fma_f32 v[100:101], v[148:149], v[116:117], v[100:101] op_sel_hi:[1,0,1]
	v_pk_fma_f32 v[102:103], v[148:149], v[116:117], v[102:103] op_sel:[0,1,0]
	v_pk_fma_f32 v[104:105], v[148:149], v[118:119], v[104:105] op_sel_hi:[1,0,1]
	v_pk_fma_f32 v[106:107], v[148:149], v[118:119], v[106:107] op_sel:[0,1,0]
	v_add_f32_dpp v151, v151, v151 row_mirror row_mask:0xf bank_mask:0xf bound_ctrl:1
	v_pk_fma_f32 v[152:153], v[148:149], v[126:127], v[150:151] op_sel_hi:[1,0,1]
	v_pk_fma_f32 v[152:153], v[124:125], v[126:127], v[152:153] op_sel:[0,1,0]
	v_cvt_pk_bf16_f32 v154, v152, v153
	s_waitcnt lgkmcnt(0)
	ds_read_b128 v[108:111], v156 offset:3104
	ds_read_b128 v[112:115], v156 offset:3360
	ds_read_b128 v[120:123], v156 offset:4128
	ds_read_b64 v[124:125], v157 offset:3104
	ds_read_b128 v[116:119], v156 offset:3872
	ds_read_b64 v[126:127], v158 offset:3104
	v_mov_b32_e32 v155, v154
	v_pk_mul_f32 v[148:149], v[100:101], v[128:129] op_sel_hi:[1,0]
	v_pk_mul_f32 v[150:151], v[100:101], v[132:133] op_sel_hi:[1,0]
	v_pk_fma_f32 v[148:149], v[102:103], v[128:129], v[148:149] op_sel:[0,1,0]
	v_pk_fma_f32 v[150:151], v[102:103], v[132:133], v[150:151] op_sel:[0,1,0]
	v_pk_fma_f32 v[148:149], v[104:105], v[130:131], v[148:149] op_sel_hi:[1,0,1]
	v_pk_fma_f32 v[150:151], v[104:105], v[134:135], v[150:151] op_sel_hi:[1,0,1]
	v_pk_fma_f32 v[148:149], v[106:107], v[130:131], v[148:149] op_sel:[0,1,0]
	v_pk_fma_f32 v[150:151], v[106:107], v[134:135], v[150:151] op_sel:[0,1,0]
	v_pk_fma_f32 v[100:101], v[144:145], v[140:141], v[100:101] op_sel_hi:[1,0,1]
	v_add_f32_dpp v148, v148, v148 quad_perm:[1,0,3,2] row_mask:0xf bank_mask:0xf bound_ctrl:1
	v_add_f32_dpp v149, v149, v149 quad_perm:[1,0,3,2] row_mask:0xf bank_mask:0xf bound_ctrl:1
	v_add_f32_dpp v150, v150, v150 quad_perm:[1,0,3,2] row_mask:0xf bank_mask:0xf bound_ctrl:1
	v_add_f32_dpp v151, v151, v151 quad_perm:[1,0,3,2] row_mask:0xf bank_mask:0xf bound_ctrl:1
	v_pk_fma_f32 v[102:103], v[144:145], v[140:141], v[102:103] op_sel:[0,1,0]
	v_add_f32_dpp v148, v148, v148 quad_perm:[2,3,0,1] row_mask:0xf bank_mask:0xf bound_ctrl:1
	v_add_f32_dpp v149, v149, v149 quad_perm:[2,3,0,1] row_mask:0xf bank_mask:0xf bound_ctrl:1
	v_add_f32_dpp v150, v150, v150 quad_perm:[2,3,0,1] row_mask:0xf bank_mask:0xf bound_ctrl:1
	v_add_f32_dpp v151, v151, v151 quad_perm:[2,3,0,1] row_mask:0xf bank_mask:0xf bound_ctrl:1
	v_pk_fma_f32 v[104:105], v[144:145], v[142:143], v[104:105] op_sel_hi:[1,0,1]
	v_add_f32_dpp v148, v148, v148 row_half_mirror row_mask:0xf bank_mask:0xf bound_ctrl:1
	v_add_f32_dpp v149, v149, v149 row_half_mirror row_mask:0xf bank_mask:0xf bound_ctrl:1
	v_add_f32_dpp v150, v150, v150 row_half_mirror row_mask:0xf bank_mask:0xf bound_ctrl:1
	v_add_f32_dpp v151, v151, v151 row_half_mirror row_mask:0xf bank_mask:0xf bound_ctrl:1
	v_pk_fma_f32 v[106:107], v[144:145], v[142:143], v[106:107] op_sel:[0,1,0]
	v_add_f32_dpp v148, v148, v148 row_mirror row_mask:0xf bank_mask:0xf bound_ctrl:1
	v_add_f32_dpp v149, v149, v149 row_mirror row_mask:0xf bank_mask:0xf bound_ctrl:1
	v_add_f32_dpp v150, v150, v150 row_mirror row_mask:0xf bank_mask:0xf bound_ctrl:1
	v_pk_fma_f32 v[100:101], v[148:149], v[136:137], v[100:101] op_sel_hi:[1,0,1]
	v_pk_fma_f32 v[102:103], v[148:149], v[136:137], v[102:103] op_sel:[0,1,0]
	v_pk_fma_f32 v[104:105], v[148:149], v[138:139], v[104:105] op_sel_hi:[1,0,1]
	v_pk_fma_f32 v[106:107], v[148:149], v[138:139], v[106:107] op_sel:[0,1,0]
	v_add_f32_dpp v151, v151, v151 row_mirror row_mask:0xf bank_mask:0xf bound_ctrl:1
	v_pk_fma_f32 v[152:153], v[148:149], v[146:147], v[150:151] op_sel_hi:[1,0,1]
	v_pk_fma_f32 v[152:153], v[144:145], v[146:147], v[152:153] op_sel:[0,1,0]
	v_cvt_pk_bf16_f32 v154, v152, v153
	s_waitcnt lgkmcnt(0)
	ds_read_b128 v[128:131], v156 offset:4656
	ds_read_b128 v[132:135], v156 offset:4912
	ds_read_b128 v[140:143], v156 offset:5680
	ds_read_b64 v[144:145], v157 offset:4656
	ds_read_b128 v[136:139], v156 offset:5424
	ds_read_b64 v[146:147], v158 offset:4656
	v_mov_b32_dpp v155, v154 row_shr:1 row_mask:0xf bank_mask:0xf
	v_pk_mul_f32 v[148:149], v[100:101], v[108:109] op_sel_hi:[1,0]
	v_pk_mul_f32 v[150:151], v[100:101], v[112:113] op_sel_hi:[1,0]
	v_pk_fma_f32 v[148:149], v[102:103], v[108:109], v[148:149] op_sel:[0,1,0]
	v_pk_fma_f32 v[150:151], v[102:103], v[112:113], v[150:151] op_sel:[0,1,0]
	v_pk_fma_f32 v[148:149], v[104:105], v[110:111], v[148:149] op_sel_hi:[1,0,1]
	v_pk_fma_f32 v[150:151], v[104:105], v[114:115], v[150:151] op_sel_hi:[1,0,1]
	v_pk_fma_f32 v[148:149], v[106:107], v[110:111], v[148:149] op_sel:[0,1,0]
	v_pk_fma_f32 v[150:151], v[106:107], v[114:115], v[150:151] op_sel:[0,1,0]
	v_pk_fma_f32 v[100:101], v[124:125], v[120:121], v[100:101] op_sel_hi:[1,0,1]
	v_add_f32_dpp v148, v148, v148 quad_perm:[1,0,3,2] row_mask:0xf bank_mask:0xf bound_ctrl:1
	v_add_f32_dpp v149, v149, v149 quad_perm:[1,0,3,2] row_mask:0xf bank_mask:0xf bound_ctrl:1
	v_add_f32_dpp v150, v150, v150 quad_perm:[1,0,3,2] row_mask:0xf bank_mask:0xf bound_ctrl:1
	v_add_f32_dpp v151, v151, v151 quad_perm:[1,0,3,2] row_mask:0xf bank_mask:0xf bound_ctrl:1
	v_pk_fma_f32 v[102:103], v[124:125], v[120:121], v[102:103] op_sel:[0,1,0]
	v_add_f32_dpp v148, v148, v148 quad_perm:[2,3,0,1] row_mask:0xf bank_mask:0xf bound_ctrl:1
	v_add_f32_dpp v149, v149, v149 quad_perm:[2,3,0,1] row_mask:0xf bank_mask:0xf bound_ctrl:1
	v_add_f32_dpp v150, v150, v150 quad_perm:[2,3,0,1] row_mask:0xf bank_mask:0xf bound_ctrl:1
	v_add_f32_dpp v151, v151, v151 quad_perm:[2,3,0,1] row_mask:0xf bank_mask:0xf bound_ctrl:1
	v_pk_fma_f32 v[104:105], v[124:125], v[122:123], v[104:105] op_sel_hi:[1,0,1]
	v_add_f32_dpp v148, v148, v148 row_half_mirror row_mask:0xf bank_mask:0xf bound_ctrl:1
	v_add_f32_dpp v149, v149, v149 row_half_mirror row_mask:0xf bank_mask:0xf bound_ctrl:1
	v_add_f32_dpp v150, v150, v150 row_half_mirror row_mask:0xf bank_mask:0xf bound_ctrl:1
	v_add_f32_dpp v151, v151, v151 row_half_mirror row_mask:0xf bank_mask:0xf bound_ctrl:1
	v_pk_fma_f32 v[106:107], v[124:125], v[122:123], v[106:107] op_sel:[0,1,0]
	v_add_f32_dpp v148, v148, v148 row_mirror row_mask:0xf bank_mask:0xf bound_ctrl:1
	v_add_f32_dpp v149, v149, v149 row_mirror row_mask:0xf bank_mask:0xf bound_ctrl:1
	v_add_f32_dpp v150, v150, v150 row_mirror row_mask:0xf bank_mask:0xf bound_ctrl:1
	v_pk_fma_f32 v[100:101], v[148:149], v[116:117], v[100:101] op_sel_hi:[1,0,1]
	v_pk_fma_f32 v[102:103], v[148:149], v[116:117], v[102:103] op_sel:[0,1,0]
	v_pk_fma_f32 v[104:105], v[148:149], v[118:119], v[104:105] op_sel_hi:[1,0,1]
	v_pk_fma_f32 v[106:107], v[148:149], v[118:119], v[106:107] op_sel:[0,1,0]
	v_add_f32_dpp v151, v151, v151 row_mirror row_mask:0xf bank_mask:0xf bound_ctrl:1
	v_pk_fma_f32 v[152:153], v[148:149], v[126:127], v[150:151] op_sel_hi:[1,0,1]
	v_pk_fma_f32 v[152:153], v[124:125], v[126:127], v[152:153] op_sel:[0,1,0]
	v_cvt_pk_bf16_f32 v154, v152, v153
	s_waitcnt lgkmcnt(0)
	ds_read_b128 v[108:111], v156 offset:6208
	ds_read_b128 v[112:115], v156 offset:6464
	ds_read_b128 v[120:123], v156 offset:7232
	ds_read_b64 v[124:125], v157 offset:6208
	ds_read_b128 v[116:119], v156 offset:6976
	ds_read_b64 v[126:127], v158 offset:6208
	v_mov_b32_dpp v155, v154 row_shr:2 row_mask:0xf bank_mask:0xf
	v_pk_mul_f32 v[148:149], v[100:101], v[128:129] op_sel_hi:[1,0]
	v_pk_mul_f32 v[150:151], v[100:101], v[132:133] op_sel_hi:[1,0]
	v_pk_fma_f32 v[148:149], v[102:103], v[128:129], v[148:149] op_sel:[0,1,0]
	v_pk_fma_f32 v[150:151], v[102:103], v[132:133], v[150:151] op_sel:[0,1,0]
	v_pk_fma_f32 v[148:149], v[104:105], v[130:131], v[148:149] op_sel_hi:[1,0,1]
	v_pk_fma_f32 v[150:151], v[104:105], v[134:135], v[150:151] op_sel_hi:[1,0,1]
	v_pk_fma_f32 v[148:149], v[106:107], v[130:131], v[148:149] op_sel:[0,1,0]
	v_pk_fma_f32 v[150:151], v[106:107], v[134:135], v[150:151] op_sel:[0,1,0]
	v_pk_fma_f32 v[100:101], v[144:145], v[140:141], v[100:101] op_sel_hi:[1,0,1]
	v_add_f32_dpp v148, v148, v148 quad_perm:[1,0,3,2] row_mask:0xf bank_mask:0xf bound_ctrl:1
	v_add_f32_dpp v149, v149, v149 quad_perm:[1,0,3,2] row_mask:0xf bank_mask:0xf bound_ctrl:1
	v_add_f32_dpp v150, v150, v150 quad_perm:[1,0,3,2] row_mask:0xf bank_mask:0xf bound_ctrl:1
	v_add_f32_dpp v151, v151, v151 quad_perm:[1,0,3,2] row_mask:0xf bank_mask:0xf bound_ctrl:1
	v_pk_fma_f32 v[102:103], v[144:145], v[140:141], v[102:103] op_sel:[0,1,0]
	v_add_f32_dpp v148, v148, v148 quad_perm:[2,3,0,1] row_mask:0xf bank_mask:0xf bound_ctrl:1
	v_add_f32_dpp v149, v149, v149 quad_perm:[2,3,0,1] row_mask:0xf bank_mask:0xf bound_ctrl:1
	v_add_f32_dpp v150, v150, v150 quad_perm:[2,3,0,1] row_mask:0xf bank_mask:0xf bound_ctrl:1
	v_add_f32_dpp v151, v151, v151 quad_perm:[2,3,0,1] row_mask:0xf bank_mask:0xf bound_ctrl:1
	v_pk_fma_f32 v[104:105], v[144:145], v[142:143], v[104:105] op_sel_hi:[1,0,1]
	v_add_f32_dpp v148, v148, v148 row_half_mirror row_mask:0xf bank_mask:0xf bound_ctrl:1
	v_add_f32_dpp v149, v149, v149 row_half_mirror row_mask:0xf bank_mask:0xf bound_ctrl:1
	v_add_f32_dpp v150, v150, v150 row_half_mirror row_mask:0xf bank_mask:0xf bound_ctrl:1
	v_add_f32_dpp v151, v151, v151 row_half_mirror row_mask:0xf bank_mask:0xf bound_ctrl:1
	v_pk_fma_f32 v[106:107], v[144:145], v[142:143], v[106:107] op_sel:[0,1,0]
	v_add_f32_dpp v148, v148, v148 row_mirror row_mask:0xf bank_mask:0xf bound_ctrl:1
	v_add_f32_dpp v149, v149, v149 row_mirror row_mask:0xf bank_mask:0xf bound_ctrl:1
	v_add_f32_dpp v150, v150, v150 row_mirror row_mask:0xf bank_mask:0xf bound_ctrl:1
	v_pk_fma_f32 v[100:101], v[148:149], v[136:137], v[100:101] op_sel_hi:[1,0,1]
	v_pk_fma_f32 v[102:103], v[148:149], v[136:137], v[102:103] op_sel:[0,1,0]
	v_pk_fma_f32 v[104:105], v[148:149], v[138:139], v[104:105] op_sel_hi:[1,0,1]
	v_pk_fma_f32 v[106:107], v[148:149], v[138:139], v[106:107] op_sel:[0,1,0]
	v_add_f32_dpp v151, v151, v151 row_mirror row_mask:0xf bank_mask:0xf bound_ctrl:1
	v_pk_fma_f32 v[152:153], v[148:149], v[146:147], v[150:151] op_sel_hi:[1,0,1]
	v_pk_fma_f32 v[152:153], v[144:145], v[146:147], v[152:153] op_sel:[0,1,0]
	v_cvt_pk_bf16_f32 v154, v152, v153
	s_waitcnt lgkmcnt(0)
	ds_read_b128 v[128:131], v156 offset:7760
	ds_read_b128 v[132:135], v156 offset:8016
	ds_read_b128 v[140:143], v156 offset:8784
	ds_read_b64 v[144:145], v157 offset:7760
	ds_read_b128 v[136:139], v156 offset:8528
	ds_read_b64 v[146:147], v158 offset:7760
	v_mov_b32_dpp v155, v154 row_shr:3 row_mask:0xf bank_mask:0xf
	v_pk_mul_f32 v[148:149], v[100:101], v[108:109] op_sel_hi:[1,0]
	v_pk_mul_f32 v[150:151], v[100:101], v[112:113] op_sel_hi:[1,0]
	v_pk_fma_f32 v[148:149], v[102:103], v[108:109], v[148:149] op_sel:[0,1,0]
	v_pk_fma_f32 v[150:151], v[102:103], v[112:113], v[150:151] op_sel:[0,1,0]
	v_pk_fma_f32 v[148:149], v[104:105], v[110:111], v[148:149] op_sel_hi:[1,0,1]
	v_pk_fma_f32 v[150:151], v[104:105], v[114:115], v[150:151] op_sel_hi:[1,0,1]
	v_pk_fma_f32 v[148:149], v[106:107], v[110:111], v[148:149] op_sel:[0,1,0]
	v_pk_fma_f32 v[150:151], v[106:107], v[114:115], v[150:151] op_sel:[0,1,0]
	v_pk_fma_f32 v[100:101], v[124:125], v[120:121], v[100:101] op_sel_hi:[1,0,1]
	v_add_f32_dpp v148, v148, v148 quad_perm:[1,0,3,2] row_mask:0xf bank_mask:0xf bound_ctrl:1
	v_add_f32_dpp v149, v149, v149 quad_perm:[1,0,3,2] row_mask:0xf bank_mask:0xf bound_ctrl:1
	v_add_f32_dpp v150, v150, v150 quad_perm:[1,0,3,2] row_mask:0xf bank_mask:0xf bound_ctrl:1
	v_add_f32_dpp v151, v151, v151 quad_perm:[1,0,3,2] row_mask:0xf bank_mask:0xf bound_ctrl:1
	v_pk_fma_f32 v[102:103], v[124:125], v[120:121], v[102:103] op_sel:[0,1,0]
	v_add_f32_dpp v148, v148, v148 quad_perm:[2,3,0,1] row_mask:0xf bank_mask:0xf bound_ctrl:1
	v_add_f32_dpp v149, v149, v149 quad_perm:[2,3,0,1] row_mask:0xf bank_mask:0xf bound_ctrl:1
	v_add_f32_dpp v150, v150, v150 quad_perm:[2,3,0,1] row_mask:0xf bank_mask:0xf bound_ctrl:1
	v_add_f32_dpp v151, v151, v151 quad_perm:[2,3,0,1] row_mask:0xf bank_mask:0xf bound_ctrl:1
	v_pk_fma_f32 v[104:105], v[124:125], v[122:123], v[104:105] op_sel_hi:[1,0,1]
	v_add_f32_dpp v148, v148, v148 row_half_mirror row_mask:0xf bank_mask:0xf bound_ctrl:1
	v_add_f32_dpp v149, v149, v149 row_half_mirror row_mask:0xf bank_mask:0xf bound_ctrl:1
	v_add_f32_dpp v150, v150, v150 row_half_mirror row_mask:0xf bank_mask:0xf bound_ctrl:1
	v_add_f32_dpp v151, v151, v151 row_half_mirror row_mask:0xf bank_mask:0xf bound_ctrl:1
	v_pk_fma_f32 v[106:107], v[124:125], v[122:123], v[106:107] op_sel:[0,1,0]
	v_add_f32_dpp v148, v148, v148 row_mirror row_mask:0xf bank_mask:0xf bound_ctrl:1
	v_add_f32_dpp v149, v149, v149 row_mirror row_mask:0xf bank_mask:0xf bound_ctrl:1
	v_add_f32_dpp v150, v150, v150 row_mirror row_mask:0xf bank_mask:0xf bound_ctrl:1
	v_pk_fma_f32 v[100:101], v[148:149], v[116:117], v[100:101] op_sel_hi:[1,0,1]
	v_pk_fma_f32 v[102:103], v[148:149], v[116:117], v[102:103] op_sel:[0,1,0]
	v_pk_fma_f32 v[104:105], v[148:149], v[118:119], v[104:105] op_sel_hi:[1,0,1]
	v_pk_fma_f32 v[106:107], v[148:149], v[118:119], v[106:107] op_sel:[0,1,0]
	v_add_f32_dpp v151, v151, v151 row_mirror row_mask:0xf bank_mask:0xf bound_ctrl:1
	v_pk_fma_f32 v[152:153], v[148:149], v[126:127], v[150:151] op_sel_hi:[1,0,1]
	v_pk_fma_f32 v[152:153], v[124:125], v[126:127], v[152:153] op_sel:[0,1,0]
	v_cvt_pk_bf16_f32 v154, v152, v153
	s_waitcnt lgkmcnt(0)
	ds_read_b128 v[108:111], v156 offset:9312
	ds_read_b128 v[112:115], v156 offset:9568
	ds_read_b128 v[120:123], v156 offset:10336
	ds_read_b64 v[124:125], v157 offset:9312
	ds_read_b128 v[116:119], v156 offset:10080
	ds_read_b64 v[126:127], v158 offset:9312
	v_mov_b32_dpp v155, v154 row_shr:4 row_mask:0xf bank_mask:0xf
	v_pk_mul_f32 v[148:149], v[100:101], v[128:129] op_sel_hi:[1,0]
	v_pk_mul_f32 v[150:151], v[100:101], v[132:133] op_sel_hi:[1,0]
	v_pk_fma_f32 v[148:149], v[102:103], v[128:129], v[148:149] op_sel:[0,1,0]
	v_pk_fma_f32 v[150:151], v[102:103], v[132:133], v[150:151] op_sel:[0,1,0]
	v_pk_fma_f32 v[148:149], v[104:105], v[130:131], v[148:149] op_sel_hi:[1,0,1]
	v_pk_fma_f32 v[150:151], v[104:105], v[134:135], v[150:151] op_sel_hi:[1,0,1]
	v_pk_fma_f32 v[148:149], v[106:107], v[130:131], v[148:149] op_sel:[0,1,0]
	v_pk_fma_f32 v[150:151], v[106:107], v[134:135], v[150:151] op_sel:[0,1,0]
	v_pk_fma_f32 v[100:101], v[144:145], v[140:141], v[100:101] op_sel_hi:[1,0,1]
	v_add_f32_dpp v148, v148, v148 quad_perm:[1,0,3,2] row_mask:0xf bank_mask:0xf bound_ctrl:1
	v_add_f32_dpp v149, v149, v149 quad_perm:[1,0,3,2] row_mask:0xf bank_mask:0xf bound_ctrl:1
	v_add_f32_dpp v150, v150, v150 quad_perm:[1,0,3,2] row_mask:0xf bank_mask:0xf bound_ctrl:1
	v_add_f32_dpp v151, v151, v151 quad_perm:[1,0,3,2] row_mask:0xf bank_mask:0xf bound_ctrl:1
	v_pk_fma_f32 v[102:103], v[144:145], v[140:141], v[102:103] op_sel:[0,1,0]
	v_add_f32_dpp v148, v148, v148 quad_perm:[2,3,0,1] row_mask:0xf bank_mask:0xf bound_ctrl:1
	v_add_f32_dpp v149, v149, v149 quad_perm:[2,3,0,1] row_mask:0xf bank_mask:0xf bound_ctrl:1
	v_add_f32_dpp v150, v150, v150 quad_perm:[2,3,0,1] row_mask:0xf bank_mask:0xf bound_ctrl:1
	v_add_f32_dpp v151, v151, v151 quad_perm:[2,3,0,1] row_mask:0xf bank_mask:0xf bound_ctrl:1
	v_pk_fma_f32 v[104:105], v[144:145], v[142:143], v[104:105] op_sel_hi:[1,0,1]
	v_add_f32_dpp v148, v148, v148 row_half_mirror row_mask:0xf bank_mask:0xf bound_ctrl:1
	v_add_f32_dpp v149, v149, v149 row_half_mirror row_mask:0xf bank_mask:0xf bound_ctrl:1
	v_add_f32_dpp v150, v150, v150 row_half_mirror row_mask:0xf bank_mask:0xf bound_ctrl:1
	v_add_f32_dpp v151, v151, v151 row_half_mirror row_mask:0xf bank_mask:0xf bound_ctrl:1
	v_pk_fma_f32 v[106:107], v[144:145], v[142:143], v[106:107] op_sel:[0,1,0]
	v_add_f32_dpp v148, v148, v148 row_mirror row_mask:0xf bank_mask:0xf bound_ctrl:1
	v_add_f32_dpp v149, v149, v149 row_mirror row_mask:0xf bank_mask:0xf bound_ctrl:1
	v_add_f32_dpp v150, v150, v150 row_mirror row_mask:0xf bank_mask:0xf bound_ctrl:1
	v_pk_fma_f32 v[100:101], v[148:149], v[136:137], v[100:101] op_sel_hi:[1,0,1]
	v_pk_fma_f32 v[102:103], v[148:149], v[136:137], v[102:103] op_sel:[0,1,0]
	v_pk_fma_f32 v[104:105], v[148:149], v[138:139], v[104:105] op_sel_hi:[1,0,1]
	v_pk_fma_f32 v[106:107], v[148:149], v[138:139], v[106:107] op_sel:[0,1,0]
	v_add_f32_dpp v151, v151, v151 row_mirror row_mask:0xf bank_mask:0xf bound_ctrl:1
	v_pk_fma_f32 v[152:153], v[148:149], v[146:147], v[150:151] op_sel_hi:[1,0,1]
	v_pk_fma_f32 v[152:153], v[144:145], v[146:147], v[152:153] op_sel:[0,1,0]
	v_cvt_pk_bf16_f32 v154, v152, v153
	s_waitcnt lgkmcnt(0)
	ds_read_b128 v[128:131], v156 offset:10864
	ds_read_b128 v[132:135], v156 offset:11120
	ds_read_b128 v[140:143], v156 offset:11888
	ds_read_b64 v[144:145], v157 offset:10864
	ds_read_b128 v[136:139], v156 offset:11632
	ds_read_b64 v[146:147], v158 offset:10864
	v_mov_b32_dpp v155, v154 row_shr:5 row_mask:0xf bank_mask:0xf
	v_pk_mul_f32 v[148:149], v[100:101], v[108:109] op_sel_hi:[1,0]
	v_pk_mul_f32 v[150:151], v[100:101], v[112:113] op_sel_hi:[1,0]
	v_pk_fma_f32 v[148:149], v[102:103], v[108:109], v[148:149] op_sel:[0,1,0]
	v_pk_fma_f32 v[150:151], v[102:103], v[112:113], v[150:151] op_sel:[0,1,0]
	v_pk_fma_f32 v[148:149], v[104:105], v[110:111], v[148:149] op_sel_hi:[1,0,1]
	v_pk_fma_f32 v[150:151], v[104:105], v[114:115], v[150:151] op_sel_hi:[1,0,1]
	v_pk_fma_f32 v[148:149], v[106:107], v[110:111], v[148:149] op_sel:[0,1,0]
	v_pk_fma_f32 v[150:151], v[106:107], v[114:115], v[150:151] op_sel:[0,1,0]
	v_pk_fma_f32 v[100:101], v[124:125], v[120:121], v[100:101] op_sel_hi:[1,0,1]
	v_add_f32_dpp v148, v148, v148 quad_perm:[1,0,3,2] row_mask:0xf bank_mask:0xf bound_ctrl:1
	v_add_f32_dpp v149, v149, v149 quad_perm:[1,0,3,2] row_mask:0xf bank_mask:0xf bound_ctrl:1
	v_add_f32_dpp v150, v150, v150 quad_perm:[1,0,3,2] row_mask:0xf bank_mask:0xf bound_ctrl:1
	v_add_f32_dpp v151, v151, v151 quad_perm:[1,0,3,2] row_mask:0xf bank_mask:0xf bound_ctrl:1
	v_pk_fma_f32 v[102:103], v[124:125], v[120:121], v[102:103] op_sel:[0,1,0]
	v_add_f32_dpp v148, v148, v148 quad_perm:[2,3,0,1] row_mask:0xf bank_mask:0xf bound_ctrl:1
	v_add_f32_dpp v149, v149, v149 quad_perm:[2,3,0,1] row_mask:0xf bank_mask:0xf bound_ctrl:1
	v_add_f32_dpp v150, v150, v150 quad_perm:[2,3,0,1] row_mask:0xf bank_mask:0xf bound_ctrl:1
	v_add_f32_dpp v151, v151, v151 quad_perm:[2,3,0,1] row_mask:0xf bank_mask:0xf bound_ctrl:1
	v_pk_fma_f32 v[104:105], v[124:125], v[122:123], v[104:105] op_sel_hi:[1,0,1]
	v_add_f32_dpp v148, v148, v148 row_half_mirror row_mask:0xf bank_mask:0xf bound_ctrl:1
	v_add_f32_dpp v149, v149, v149 row_half_mirror row_mask:0xf bank_mask:0xf bound_ctrl:1
	v_add_f32_dpp v150, v150, v150 row_half_mirror row_mask:0xf bank_mask:0xf bound_ctrl:1
	v_add_f32_dpp v151, v151, v151 row_half_mirror row_mask:0xf bank_mask:0xf bound_ctrl:1
	v_pk_fma_f32 v[106:107], v[124:125], v[122:123], v[106:107] op_sel:[0,1,0]
	v_add_f32_dpp v148, v148, v148 row_mirror row_mask:0xf bank_mask:0xf bound_ctrl:1
	v_add_f32_dpp v149, v149, v149 row_mirror row_mask:0xf bank_mask:0xf bound_ctrl:1
	v_add_f32_dpp v150, v150, v150 row_mirror row_mask:0xf bank_mask:0xf bound_ctrl:1
	v_pk_fma_f32 v[100:101], v[148:149], v[116:117], v[100:101] op_sel_hi:[1,0,1]
	v_pk_fma_f32 v[102:103], v[148:149], v[116:117], v[102:103] op_sel:[0,1,0]
	v_pk_fma_f32 v[104:105], v[148:149], v[118:119], v[104:105] op_sel_hi:[1,0,1]
	v_pk_fma_f32 v[106:107], v[148:149], v[118:119], v[106:107] op_sel:[0,1,0]
	v_add_f32_dpp v151, v151, v151 row_mirror row_mask:0xf bank_mask:0xf bound_ctrl:1
	v_pk_fma_f32 v[152:153], v[148:149], v[126:127], v[150:151] op_sel_hi:[1,0,1]
	v_pk_fma_f32 v[152:153], v[124:125], v[126:127], v[152:153] op_sel:[0,1,0]
	v_cvt_pk_bf16_f32 v154, v152, v153
	s_waitcnt lgkmcnt(0)
	ds_read_b128 v[204:207], v156 offset:11376
	s_nop 0
	v_mov_b32_dpp v155, v154 row_shr:6 row_mask:0xf bank_mask:0xf
	v_pk_mul_f32 v[148:149], v[100:101], v[128:129] op_sel_hi:[1,0]
	v_pk_mul_f32 v[150:151], v[100:101], v[132:133] op_sel_hi:[1,0]
	v_pk_fma_f32 v[148:149], v[102:103], v[128:129], v[148:149] op_sel:[0,1,0]
	v_pk_fma_f32 v[150:151], v[102:103], v[132:133], v[150:151] op_sel:[0,1,0]
	v_pk_fma_f32 v[148:149], v[104:105], v[130:131], v[148:149] op_sel_hi:[1,0,1]
	v_pk_fma_f32 v[150:151], v[104:105], v[134:135], v[150:151] op_sel_hi:[1,0,1]
	v_pk_fma_f32 v[148:149], v[106:107], v[130:131], v[148:149] op_sel:[0,1,0]
	v_pk_fma_f32 v[150:151], v[106:107], v[134:135], v[150:151] op_sel:[0,1,0]
	v_pk_fma_f32 v[100:101], v[144:145], v[140:141], v[100:101] op_sel_hi:[1,0,1]
	v_add_f32_dpp v148, v148, v148 quad_perm:[1,0,3,2] row_mask:0xf bank_mask:0xf bound_ctrl:1
	v_add_f32_dpp v149, v149, v149 quad_perm:[1,0,3,2] row_mask:0xf bank_mask:0xf bound_ctrl:1
	v_add_f32_dpp v150, v150, v150 quad_perm:[1,0,3,2] row_mask:0xf bank_mask:0xf bound_ctrl:1
	v_add_f32_dpp v151, v151, v151 quad_perm:[1,0,3,2] row_mask:0xf bank_mask:0xf bound_ctrl:1
	v_pk_fma_f32 v[102:103], v[144:145], v[140:141], v[102:103] op_sel:[0,1,0]
	v_add_f32_dpp v148, v148, v148 quad_perm:[2,3,0,1] row_mask:0xf bank_mask:0xf bound_ctrl:1
	v_add_f32_dpp v149, v149, v149 quad_perm:[2,3,0,1] row_mask:0xf bank_mask:0xf bound_ctrl:1
	v_add_f32_dpp v150, v150, v150 quad_perm:[2,3,0,1] row_mask:0xf bank_mask:0xf bound_ctrl:1
	v_add_f32_dpp v151, v151, v151 quad_perm:[2,3,0,1] row_mask:0xf bank_mask:0xf bound_ctrl:1
	v_pk_fma_f32 v[104:105], v[144:145], v[142:143], v[104:105] op_sel_hi:[1,0,1]
	v_add_f32_dpp v148, v148, v148 row_half_mirror row_mask:0xf bank_mask:0xf bound_ctrl:1
	v_add_f32_dpp v149, v149, v149 row_half_mirror row_mask:0xf bank_mask:0xf bound_ctrl:1
	v_add_f32_dpp v150, v150, v150 row_half_mirror row_mask:0xf bank_mask:0xf bound_ctrl:1
	v_add_f32_dpp v151, v151, v151 row_half_mirror row_mask:0xf bank_mask:0xf bound_ctrl:1
	v_pk_fma_f32 v[106:107], v[144:145], v[142:143], v[106:107] op_sel:[0,1,0]
	v_add_f32_dpp v148, v148, v148 row_mirror row_mask:0xf bank_mask:0xf bound_ctrl:1
	v_add_f32_dpp v149, v149, v149 row_mirror row_mask:0xf bank_mask:0xf bound_ctrl:1
	v_add_f32_dpp v150, v150, v150 row_mirror row_mask:0xf bank_mask:0xf bound_ctrl:1
	v_pk_fma_f32 v[100:101], v[148:149], v[136:137], v[100:101] op_sel_hi:[1,0,1]
	v_pk_fma_f32 v[102:103], v[148:149], v[136:137], v[102:103] op_sel:[0,1,0]
	v_pk_fma_f32 v[104:105], v[148:149], v[138:139], v[104:105] op_sel_hi:[1,0,1]
	v_pk_fma_f32 v[106:107], v[148:149], v[138:139], v[106:107] op_sel:[0,1,0]
	v_add_f32_dpp v151, v151, v151 row_mirror row_mask:0xf bank_mask:0xf bound_ctrl:1
	v_pk_fma_f32 v[152:153], v[148:149], v[146:147], v[150:151] op_sel_hi:[1,0,1]
	v_pk_fma_f32 v[152:153], v[144:145], v[146:147], v[152:153] op_sel:[0,1,0]
	v_cvt_pk_bf16_f32 v154, v152, v153
	s_waitcnt lgkmcnt(0)
	v_pk_mul_f32 v[100:101], v[100:101], v[204:205] op_sel_hi:[1,0]
	v_pk_mul_f32 v[102:103], v[102:103], v[204:205] op_sel:[0,1]
	v_pk_mul_f32 v[104:105], v[104:105], v[206:207] op_sel_hi:[1,0]
	v_pk_mul_f32 v[106:107], v[106:107], v[206:207] op_sel:[0,1]
	v_mov_b32_dpp v155, v154 row_shr:7 row_mask:0xf bank_mask:0xf
	s_mov_b32 s0, 0xff00ff
	s_mov_b32 s1, 0xff00ff
	s_mov_b64 exec, s[0:1]
	global_store_dword v234, v155, s[100:101]
	s_mov_b64 exec, -1
	v_mov_b32_e32 v236, v100
	v_mov_b32_e32 v240, v101
	v_mov_b32_e32 v237, v102
	v_mov_b32_e32 v241, v103
	v_mov_b32_e32 v238, v104
	v_mov_b32_e32 v242, v105
	v_mov_b32_e32 v239, v106
	v_mov_b32_e32 v243, v107
	global_store_dwordx4 v233, v[236:239], s[96:97]
	global_store_dwordx4 v233, v[240:243], s[96:97] offset:256
	s_xor_b32 s99, s99, 0x3080
	s_cmpk_lt_i32 s53, 0x800
	s_cbranch_scc1 .Lrws_unit
	s_waitcnt lgkmcnt(0)
	s_barrier
